# speedup vs baseline: 1.0142x; 1.0142x over previous
; template <int DUMMY>
; __device__ void ssd_item(const Params& p, int item) {
;     ...
;     {
;       const int sfb = (wid & 1) * 2;
;       f32x4 cb[2];
;       cb[0] = f32x4{0.f, 0.f, 0.f, 0.f};
;       cb[1] = f32x4{0.f, 0.f, 0.f, 0.f};
; #pragma unroll
;       for (int ks = 0; ks < 4; ++ks) {
;         bf16x8 a = *(const bf16x8*)(Cs + (lf * 16 + fr) * 136 + ks * 32 + g4 * 8);
; #pragma unroll
;         for (int j = 0; j < 2; ++j) {
;           bf16x8 bb = *(const bf16x8*)(Bs + ((sfb + j) * 16 + fr) * 136 + ks * 32 + g4 * 8);
;           cb[j] = __builtin_amdgcn_mfma_f32_16x16x32_bf16(a, bb, cb[j], 0, 0, 0);
;         }
;       }
; #pragma unroll
;       for (int j = 0; j < 2; ++j) {
;         int s_ = (sfb + j) * 16 + fr;
;         float cs_s = cs[s_];
; #pragma unroll
;         for (int r = 0; r < 4; ++r) {
;           int l_ = lf * 16 + g4 * 4 + r;
;           float gv = (s_ <= l_) ? cb[j][r] * __expf(cs[l_] - cs_s) : 0.f;
;           Gs[l_ * 72 + s_] = f2bf(gv);
;         }
;       }
;     }
.LBB0_1051:
	s_or_b64 exec, exec, s[30:31]
	s_setprio 1
	v_add3_u32 v42, s3, v158, v161
	ds_read_b128 v[32:35], v42
	ds_read_b128 v[36:39], v154 offset:17408
	ds_read_b128 v[178:181], v154 offset:21760
	ds_read_b128 v[182:185], v42 offset:64
	ds_read_b128 v[186:189], v154 offset:17472
	ds_read_b128 v[220:223], v154 offset:21824
	ds_read_b128 v[224:227], v42 offset:128
	ds_read_b128 v[228:231], v154 offset:17536
	v_lshl_add_u32 v100, v121, 2, s52
	v_mov_b32_e32 v177, 0
	v_lshl_add_u32 v87, v119, 2, s52
	s_waitcnt lgkmcnt(6)
	v_mfma_f32_16x16x32_bf16 v[36:39], v[32:35], v[36:39], 0
	s_waitcnt lgkmcnt(5)
	v_mfma_f32_16x16x32_bf16 v[32:35], v[32:35], v[178:181], 0
	ds_read_b128 v[232:235], v154 offset:21888
	ds_read_b128 v[236:239], v42 offset:192
	ds_read_b128 v[240:243], v154 offset:17600
	ds_read_b128 v[244:247], v154 offset:21952
	ds_read_b32 v216, v87
	ds_read_b32 v217, v87 offset:4
	ds_read_b32 v218, v87 offset:8
	ds_read_b32 v219, v87 offset:12
	ds_read_b32 v101, v100
	s_waitcnt lgkmcnt(12)
	v_mfma_f32_16x16x32_bf16 v[36:39], v[182:185], v[186:189], v[36:39]
	s_waitcnt lgkmcnt(11)
	v_mfma_f32_16x16x32_bf16 v[32:35], v[182:185], v[220:223], v[32:35]
	s_waitcnt lgkmcnt(9)
	v_mfma_f32_16x16x32_bf16 v[36:39], v[224:227], v[228:231], v[36:39]
	s_waitcnt lgkmcnt(8)
	v_mfma_f32_16x16x32_bf16 v[32:35], v[224:227], v[232:235], v[32:35]
	s_waitcnt lgkmcnt(6)
	v_mfma_f32_16x16x32_bf16 v[36:39], v[236:239], v[240:243], v[36:39]
	s_waitcnt lgkmcnt(5)
	v_mfma_f32_16x16x32_bf16 v[32:35], v[236:239], v[244:247], v[32:35]
	s_waitcnt lgkmcnt(0)
	v_mov_b32_e32 v178, 0
	s_and_saveexec_b64 s[30:31], s[6:7]
	s_cbranch_execz .LBB0_1053
	v_mov_b32_e32 v178, v216
	v_sub_f32_e32 v178, v178, v101
	v_mul_f32_e32 v178, 0x3fb8aa3b, v178
	v_exp_f32_e32 v178, v178
	s_nop 0
	v_mul_f32_e32 v36, v36, v178
	v_cvt_pk_bf16_f32 v178, v36, s0
.LBB0_1053:
	s_or_b64 exec, exec, s[30:31]
	ds_write_b16 v124, v178
	s_and_saveexec_b64 s[30:31], s[8:9]
	s_cbranch_execz .LBB0_1055
	v_mov_b32_e32 v36, v217
	v_sub_f32_e32 v36, v36, v101
	v_mul_f32_e32 v36, 0x3fb8aa3b, v36
	v_exp_f32_e32 v36, v36
	s_nop 0
	v_mul_f32_e32 v36, v37, v36
	v_cvt_pk_bf16_f32 v177, v36, s0
.LBB0_1055:
	s_or_b64 exec, exec, s[30:31]
	v_mov_b32_e32 v37, 0
	v_mov_b32_e32 v36, 0
	ds_write_b16 v125, v177
	s_and_saveexec_b64 s[30:31], s[10:11]
	s_cbranch_execz .LBB0_1057
	v_mov_b32_e32 v36, v218
	v_sub_f32_e32 v36, v36, v101
	v_mul_f32_e32 v36, 0x3fb8aa3b, v36
	v_exp_f32_e32 v36, v36
	s_nop 0
	v_mul_f32_e32 v36, v38, v36
	v_cvt_pk_bf16_f32 v36, v36, s0
.LBB0_1057:
	s_or_b64 exec, exec, s[30:31]
	ds_write_b16 v126, v36
	s_and_saveexec_b64 s[30:31], s[12:13]
	s_cbranch_execz .LBB0_1059
	v_mov_b32_e32 v36, v219
	v_sub_f32_e32 v36, v36, v101
	v_mul_f32_e32 v36, 0x3fb8aa3b, v36
	v_exp_f32_e32 v36, v36
	s_nop 0
	v_mul_f32_e32 v36, v39, v36
	v_cvt_pk_bf16_f32 v37, v36, s0
.LBB0_1059:
	s_or_b64 exec, exec, s[30:31]
	ds_read_b32 v36, v100 offset:64
	ds_write_b16 v127, v37
	v_mov_b32_e32 v37, 0
	v_mov_b32_e32 v38, 0
	s_waitcnt lgkmcnt(0)
	s_and_saveexec_b64 s[30:31], s[14:15]
	s_cbranch_execz .LBB0_1061
	v_mov_b32_e32 v38, v216
	v_sub_f32_e32 v38, v38, v36
	v_mul_f32_e32 v38, 0x3fb8aa3b, v38
	v_exp_f32_e32 v38, v38
	s_nop 0
	v_mul_f32_e32 v32, v32, v38
	v_cvt_pk_bf16_f32 v38, v32, s0
.LBB0_1061:
	s_or_b64 exec, exec, s[30:31]
	ds_write_b16 v128, v38
	s_and_saveexec_b64 s[30:31], s[16:17]
	s_cbranch_execz .LBB0_1063
	v_mov_b32_e32 v32, v217
	v_sub_f32_e32 v32, v32, v36
	v_mul_f32_e32 v32, 0x3fb8aa3b, v32
	v_exp_f32_e32 v32, v32
	s_nop 0
	v_mul_f32_e32 v32, v33, v32
	v_cvt_pk_bf16_f32 v37, v32, s0
.LBB0_1063:
	s_or_b64 exec, exec, s[30:31]
	v_mov_b32_e32 v32, 0
	v_mov_b32_e32 v33, 0
	ds_write_b16 v129, v37
	s_and_saveexec_b64 s[30:31], s[18:19]
	s_cbranch_execz .LBB0_1065
	v_mov_b32_e32 v33, v218
	v_sub_f32_e32 v33, v33, v36
	v_mul_f32_e32 v33, 0x3fb8aa3b, v33
	v_exp_f32_e32 v33, v33
	s_nop 0
	v_mul_f32_e32 v33, v34, v33
	v_cvt_pk_bf16_f32 v33, v33, s0
.LBB0_1065:
	s_or_b64 exec, exec, s[30:31]
	ds_write_b16 v130, v33
	s_and_saveexec_b64 s[30:31], s[20:21]
	s_cbranch_execz .LBB0_1067
	v_mov_b32_e32 v32, v219
	v_sub_f32_e32 v32, v32, v36
	v_mul_f32_e32 v32, 0x3fb8aa3b, v32
	v_exp_f32_e32 v32, v32
	s_nop 0
	v_mul_f32_e32 v32, v35, v32
	v_cvt_pk_bf16_f32 v32, v32, s0
; __device__ __forceinline__ float bf2f(u16 h) { return __uint_as_float(((unsigned)h) << 16); }
; __device__ __forceinline__ float siluf_(float v) { return v * __builtin_amdgcn_rcpf(1.f + __expf(-v)); }
; template <int DUMMY>
; __device__ void ssd_item(const Params& p, int item) {
;     ...
;     {
;       float dec = __expf(cs[63]);
; #pragma unroll
;       for (int j = 0; j < 2; ++j) {
;         accS[j][0] *= dec; accS[j][1] *= dec; accS[j][2] *= dec; accS[j][3] *= dec;
;       }
; #pragma unroll
;       for (int ks = 0; ks < 2; ++ks) {
;         bf16x8 a = *(const bf16x8*)(xwT + (pf * 16 + fr) * 72 + ks * 32 + g4 * 8);
; #pragma unroll
;         for (int j = 0; j < 2; ++j) {
;           bf16x8 bb = *(const bf16x8*)(BTs + ((nf0 + j) * 16 + fr) * 72 + ks * 32 + g4 * 8);
;           accS[j] = __builtin_amdgcn_mfma_f32_16x16x32_bf16(a, bb, accS[j], 0, 0, 0);
;         }
;       }
;     }
;     __builtin_amdgcn_s_setprio(0);
;     RAW_BARRIER();
;     __builtin_amdgcn_s_setprio(1);
;     {
;       f32x4 yd = {0.f, 0.f, 0.f, 0.f}, yo = {0.f, 0.f, 0.f, 0.f};
; #pragma unroll
;       for (int ks = 0; ks < 2; ++ks) {
;         bf16x8 a = *(const bf16x8*)(Gs + (lf * 16 + fr) * 72 + ks * 32 + g4 * 8);
;         bf16x8 bb = *(const bf16x8*)(xdT + (pf * 16 + fr) * 72 + ks * 32 + g4 * 8);
;         yd = __builtin_amdgcn_mfma_f32_16x16x32_bf16(a, bb, yd, 0, 0, 0);
;       }
; #pragma unroll
;       for (int ks = 0; ks < 4; ++ks) {
;         bf16x8 a = *(const bf16x8*)(Cs + (lf * 16 + fr) * 136 + ks * 32 + g4 * 8);
;         bf16x8 bb = *(const bf16x8*)(Sb + (pf * 16 + fr) * 136 + ks * 32 + g4 * 8);
;         yo = __builtin_amdgcn_mfma_f32_16x16x32_bf16(a, bb, yo, 0, 0, 0);
;       }
;       __builtin_amdgcn_s_setprio(0);
;       bf16x4 xs4 = *(const bf16x4*)(xT + (pf * 16 + fr) * 72 + lf * 16 + g4 * 4);
; #pragma unroll
;       for (int r = 0; r < 4; ++r) {
;         int l_ = lf * 16 + g4 * 4 + r;
;         float y = yd[r] + __expf(cs[l_]) * yo[r] + Dh * bf2f((u16)xs4[r]);
;         y *= siluf_(bf2f(zcur[r]));
;         ytile[l_ * 36 + pf * 16 + fr] = f2bf(y);
;         float sq = row16_sum(y * y);
;         if (fr == 0) sqs[wid * 16 + g4 * 4 + r] = sq;
;       }
.LBB0_1067:
	s_or_b64 exec, exec, s[30:31]
	v_mov_b32_e32 v33, s52
	ds_read_b32 v100, v33 offset:252
	ds_write_b16 v131, v32
	ds_read_b128 v[32:35], v134 offset:57856
	s_waitcnt lgkmcnt(7)
	ds_read_b128 v[36:39], v136 offset:34816
	ds_read_b128 v[178:181], v138 offset:34816
	ds_read_b128 v[182:185], v134 offset:57920
	ds_read_b128 v[186:189], v136 offset:34880
	s_waitcnt lgkmcnt(6)
	v_mul_f32_e32 v100, 0x3fb8aa3b, v100
	v_exp_f32_e32 v100, v100
	s_nop 0
	v_pk_mul_f32 v[6:7], v[6:7], v[100:101] op_sel_hi:[1,0]
	v_pk_mul_f32 v[4:5], v[4:5], v[100:101] op_sel_hi:[1,0]
	v_pk_mul_f32 v[2:3], v[2:3], v[100:101] op_sel_hi:[1,0]
	v_pk_mul_f32 v[0:1], v[0:1], v[100:101] op_sel_hi:[1,0]
	s_waitcnt lgkmcnt(3)
	v_mfma_f32_16x16x32_bf16 v[4:7], v[32:35], v[36:39], v[4:7]
	ds_read_b128 v[36:39], v138 offset:34880
	s_waitcnt lgkmcnt(3)
	v_mfma_f32_16x16x32_bf16 v[0:3], v[32:35], v[178:181], v[0:3]
	s_waitcnt lgkmcnt(1)
	v_mfma_f32_16x16x32_bf16 v[4:7], v[182:185], v[186:189], v[4:7]
	s_waitcnt lgkmcnt(0)
	v_mfma_f32_16x16x32_bf16 v[0:3], v[182:185], v[36:39], v[0:3]
	s_setprio 0
	s_waitcnt lgkmcnt(0)
	s_barrier
	s_setprio 1
	ds_read_b128 v[32:35], v42
	v_add3_u32 v100, s78, v162, v161
	ds_read_b128 v[36:39], v100
	ds_read_b128 v[178:181], v132
	ds_read_b128 v[182:185], v42 offset:64
	ds_read_b128 v[186:189], v100 offset:64
	v_add3_u32 v101, s53, v160, v161
	s_waitcnt lgkmcnt(3)
	v_mfma_f32_16x16x32_bf16 v[32:35], v[32:35], v[36:39], 0
	ds_read_b128 v[36:39], v101
	ds_read_b128 v[190:193], v132 offset:64
	ds_read_b128 v[194:197], v101 offset:64
	s_waitcnt lgkmcnt(2)
	v_mfma_f32_16x16x32_bf16 v[178:181], v[178:181], v[36:39], 0
	ds_read_b128 v[36:39], v42 offset:128
	ds_read_b128 v[198:201], v42 offset:192
	v_mfma_f32_16x16x32_bf16 v[32:35], v[182:185], v[186:189], v[32:35]
	ds_read_b128 v[182:185], v100 offset:128
	ds_read_b128 v[186:189], v100 offset:192
	s_waitcnt lgkmcnt(1)
	v_mfma_f32_16x16x32_bf16 v[32:35], v[36:39], v[182:185], v[32:35]
	s_waitcnt lgkmcnt(0)
	v_mfma_f32_16x16x32_bf16 v[36:39], v[198:201], v[186:189], v[32:35]
	v_mfma_f32_16x16x32_bf16 v[32:35], v[190:193], v[194:197], v[178:181]
	s_setprio 0
	v_add_u32_e32 v42, s77, v160
	v_add3_u32 v42, v42, v163, v164
	v_mov_b32_e32 v177, v216
	ds_read_b64 v[100:101], v42
	s_waitcnt vmcnt(14)
	v_lshlrev_b32_e32 v42, 16, v167
	v_mul_f32_e32 v167, 0xbfb8aa3b, v42
	v_exp_f32_e32 v167, v167
	s_waitcnt lgkmcnt(1)
	v_mul_f32_e32 v177, 0x3fb8aa3b, v177
	v_exp_f32_e32 v177, v177
	v_add_f32_e32 v167, 1.0, v167
	v_rcp_f32_e32 v167, v167
	v_fma_f32 v32, v36, v177, v32
	s_waitcnt lgkmcnt(0)
	v_lshlrev_b32_e32 v36, 16, v100
	v_fmac_f32_e32 v32, v43, v36
	v_mul_f32_e32 v36, v167, v42
	v_mul_f32_e32 v32, v36, v32
	v_cvt_pk_bf16_f32 v36, v32, s0
	ds_write_b16 v123, v36
	v_mul_f32_e32 v36, v32, v32
	s_nop 1
	v_mov_b32_dpp v36, v36 quad_perm:[1,0,3,2] row_mask:0xf bank_mask:0xf bound_ctrl:1
	v_fmac_f32_e32 v36, v32, v32
	s_nop 1
	v_add_f32_dpp v32, v36, v36 quad_perm:[2,3,0,1] row_mask:0xf bank_mask:0xf bound_ctrl:1
	s_nop 1
	v_add_f32_dpp v32, v32, v32 row_half_mirror row_mask:0xf bank_mask:0xf bound_ctrl:1
	s_nop 1
	v_mov_b32_dpp v36, v32 row_mirror row_mask:0xf bank_mask:0xf bound_ctrl:1
	s_and_saveexec_b64 s[30:31], s[0:1]
	v_add_f32_e32 v32, v32, v36
	ds_write_b32 v122, v32
	s_or_b64 exec, exec, s[30:31]
	s_waitcnt vmcnt(13)
	v_lshlrev_b32_e32 v166, 16, v166
	v_mov_b32_e32 v32, v217
	v_mul_f32_e32 v36, 0xbfb8aa3b, v166
	v_exp_f32_e32 v36, v36
	v_and_b32_e32 v167, 0xffff0000, v100
	s_waitcnt lgkmcnt(0)
	v_mul_f32_e32 v32, 0x3fb8aa3b, v32
	v_add_f32_e32 v36, 1.0, v36
	v_exp_f32_e32 v32, v32
	v_rcp_f32_e32 v42, v36
	v_fma_f32 v36, v37, v32, v33
	v_pk_mul_f32 v[32:33], v[42:43], v[166:167]
	s_nop 0
	v_add_f32_e32 v33, v33, v36
	v_mul_f32_e32 v32, v32, v33
	v_cvt_pk_bf16_f32 v33, v32, s0
	v_mul_f32_e32 v36, v32, v32
	ds_write_b16 v123, v33 offset:72
	s_nop 0
	v_mov_b32_dpp v33, v36 quad_perm:[1,0,3,2] row_mask:0xf bank_mask:0xf bound_ctrl:1
	v_fmac_f32_e32 v33, v32, v32
	s_nop 1
	v_add_f32_dpp v32, v33, v33 quad_perm:[2,3,0,1] row_mask:0xf bank_mask:0xf bound_ctrl:1
	s_nop 1
	v_add_f32_dpp v32, v32, v32 row_half_mirror row_mask:0xf bank_mask:0xf bound_ctrl:1
	s_nop 1
	v_mov_b32_dpp v33, v32 row_mirror row_mask:0xf bank_mask:0xf bound_ctrl:1
	s_and_saveexec_b64 s[30:31], s[0:1]
	v_add_f32_e32 v32, v32, v33
	ds_write_b32 v122, v32 offset:4
	s_or_b64 exec, exec, s[30:31]
	v_mov_b32_e32 v33, v218
	s_waitcnt vmcnt(12)
	v_lshlrev_b32_e32 v32, 16, v165
	v_mul_f32_e32 v36, 0xbfb8aa3b, v32
	v_exp_f32_e32 v36, v36
	s_waitcnt lgkmcnt(0)
; __device__ __forceinline__ float bf2f(u16 h) { return __uint_as_float(((unsigned)h) << 16); }
; __device__ __forceinline__ float siluf_(float v) { return v * __builtin_amdgcn_rcpf(1.f + __expf(-v)); }
; template <int DUMMY>
; __device__ void ssd_item(const Params& p, int item) {
;     ...
;     for (int r = 0; r < 4; ++r) zcur[r] = znext[r];
;     if (c > 1) {
;       const size_t yi = (tb + (c - 2) * 64 + (tid >> 3)) * 4096 + h * 64 + ph * 32 + (tid & 7) * 4;
;       *(i32x2*)(zyo + (yi & omask)) = ypend;
;     }
;     if (c + 1 < 128) {
;       load_raw(c + 1);
;       const size_t zn = zbase + (size_t)64 * 4096;
; #pragma unroll
;       for (int r = 0; r < 4; ++r) znext[r] = zy[zn + (size_t)r * 4096];
;     ...
; #pragma unroll
;       for (int r = 0; r < 4; ++r) {
;         int l_ = lf * 16 + g4 * 4 + r;
;         float y = yd[r] + __expf(cs[l_]) * yo[r] + Dh * bf2f((u16)xs4[r]);
;         y *= siluf_(bf2f(zcur[r]));
;         ytile[l_ * 36 + pf * 16 + fr] = f2bf(y);
;         float sq = row16_sum(y * y);
;         if (fr == 0) sqs[wid * 16 + g4 * 4 + r] = sq;
;       }
;       zbase += (size_t)64 * 4096;
;     }
;     cur3 = nxt3;
	v_mul_f32_e32 v33, 0x3fb8aa3b, v33
	v_exp_f32_e32 v37, v33
	v_add_f32_e32 v33, 1.0, v36
	v_rcp_f32_e32 v42, v33
	v_lshlrev_b32_e32 v33, 16, v101
	v_fma_f32 v34, v38, v37, v34
	v_pk_mul_f32 v[32:33], v[42:43], v[32:33]
	s_nop 0
	v_add_f32_e32 v33, v33, v34
	v_mul_f32_e32 v32, v32, v33
	v_cvt_pk_bf16_f32 v33, v32, s0
	v_mul_f32_e32 v34, v32, v32
	ds_write_b16 v123, v33 offset:144
	s_nop 0
	v_mov_b32_dpp v33, v34 quad_perm:[1,0,3,2] row_mask:0xf bank_mask:0xf bound_ctrl:1
	v_fmac_f32_e32 v33, v32, v32
	s_nop 1
	v_add_f32_dpp v32, v33, v33 quad_perm:[2,3,0,1] row_mask:0xf bank_mask:0xf bound_ctrl:1
	s_nop 1
	v_add_f32_dpp v32, v32, v32 row_half_mirror row_mask:0xf bank_mask:0xf bound_ctrl:1
	s_nop 1
	v_mov_b32_dpp v33, v32 row_mirror row_mask:0xf bank_mask:0xf bound_ctrl:1
	s_and_saveexec_b64 s[30:31], s[0:1]
	v_add_f32_e32 v32, v32, v33
	ds_write_b32 v122, v32 offset:8
	s_or_b64 exec, exec, s[30:31]
	v_mov_b32_e32 v33, v219
	s_waitcnt vmcnt(11)
	v_lshlrev_b32_e32 v32, 16, v75
	v_mul_f32_e32 v34, 0xbfb8aa3b, v32
	v_exp_f32_e32 v34, v34
	s_waitcnt lgkmcnt(0)
	v_mul_f32_e32 v33, 0x3fb8aa3b, v33
	v_exp_f32_e32 v36, v33
	v_add_f32_e32 v33, 1.0, v34
	v_rcp_f32_e32 v42, v33
	v_and_b32_e32 v33, 0xffff0000, v101
	v_fmac_f32_e32 v35, v39, v36
	v_pk_mul_f32 v[32:33], v[42:43], v[32:33]
	s_nop 0
	v_add_f32_e32 v33, v33, v35
	v_mul_f32_e32 v32, v32, v33
	v_cvt_pk_bf16_f32 v33, v32, s0
	v_mul_f32_e32 v34, v32, v32
	ds_write_b16 v123, v33 offset:216
	s_nop 0
	v_mov_b32_dpp v33, v34 quad_perm:[1,0,3,2] row_mask:0xf bank_mask:0xf bound_ctrl:1
	v_fmac_f32_e32 v33, v32, v32
	s_nop 1
	v_add_f32_dpp v32, v33, v33 quad_perm:[2,3,0,1] row_mask:0xf bank_mask:0xf bound_ctrl:1
	s_nop 1
	v_add_f32_dpp v32, v32, v32 row_half_mirror row_mask:0xf bank_mask:0xf bound_ctrl:1
	s_nop 1
	v_mov_b32_dpp v33, v32 row_mirror row_mask:0xf bank_mask:0xf bound_ctrl:1
	s_and_saveexec_b64 s[30:31], s[0:1]
	v_add_f32_e32 v32, v32, v33
	ds_write_b32 v122, v32 offset:12
	s_or_b64 exec, exec, s[30:31]
	s_add_u32 s70, s70, 0x40000
	s_addc_u32 s71, s71, 0
	s_mov_b64 s[30:31], 0x4000
	s_add_i32 s76, s76, 1
	s_waitcnt vmcnt(4)
	v_perm_b32 v42, v40, v176, s94
	v_perm_b32 v100, v176, v175, s94
	v_perm_b32 v101, v175, v173, s94
	v_perm_b32 v173, v173, v174, s94
	v_perm_b32 v171, v172, v171, s94
	v_lshl_add_u64 v[84:85], v[84:85], 0, s[60:61]
	v_add_u32_e32 v86, 64, v86
	v_lshl_add_u64 v[92:93], v[92:93], 0, s[30:31]
	v_lshl_add_u64 v[94:95], v[94:95], 0, s[62:63]
	v_lshl_add_u64 v[96:97], v[96:97], 0, s[62:63]
	s_cmp_eq_u32 s70, 0x1f00000
	v_lshl_add_u64 v[98:99], v[98:99], 0, s[60:61]
	s_waitcnt vmcnt(0)
	v_mov_b32_e32 v118, v255
	s_cbranch_scc1 .LBB0_1077
	s_waitcnt vmcnt(0)
	v_mov_b32_e32 v75, v49
	v_mov_b32_e32 v165, v168
	v_mov_b32_e32 v166, v169
	v_mov_b32_e32 v167, v170
	v_lshl_add_u64 v[224:225], v[78:79], 0, s[70:71]
	v_lshl_add_u64 v[226:227], v[80:81], 0, s[70:71]
	v_add_co_u32_e32 v224, vcc, 0x100000, v224
	s_nop 1
	v_addc_co_u32_e32 v225, vcc, 0, v225, vcc
	v_add_co_u32_e32 v226, vcc, 0x100000, v226
	s_nop 1
	v_addc_co_u32_e32 v227, vcc, 0, v227, vcc
	global_load_dword v228, v[224:225], off
	global_load_dword v228, v[224:225], off offset:2048
	global_load_dword v228, v[226:227], off
	global_load_dword v228, v[226:227], off offset:2048
	v_add_u32_e32 v224, 61, v86
	v_mov_b32_e32 v225, v41
	v_lshl_add_u64 v[224:225], s[64:65], 0, v[224:225]
	v_mad_u64_u32 v[226:227], s[72:73], v224, s86, v[66:67]
	v_mad_i32_i24 v227, v225, s86, v227
	global_load_ushort v228, v[226:227], off
	v_add_co_u32_e32 v226, vcc, 0x3000, v226
	s_nop 1
	v_addc_co_u32_e32 v227, vcc, 0, v227, vcc
	global_load_ushort v228, v[226:227], off
	v_add_co_u32_e32 v226, vcc, 0x3000, v226
	s_nop 1
	v_addc_co_u32_e32 v227, vcc, 0, v227, vcc
	global_load_ushort v228, v[226:227], off
	v_add_co_u32_e32 v226, vcc, 0x3000, v226
	s_nop 1
	v_addc_co_u32_e32 v227, vcc, 0, v227, vcc
	global_load_ushort v228, v[226:227], off
	v_lshl_add_u64 v[224:225], v[84:85], 0, s[60:61]
	v_lshl_add_u64 v[224:225], s[42:43], 0, v[224:225]
	v_add_co_u32_e32 v226, vcc, 0xb280000, v224
	s_nop 1
	v_addc_co_u32_e32 v227, vcc, 0, v225, vcc
	global_load_ushort v228, v[226:227], off
	v_add_co_u32_e32 v226, vcc, 0xb282000, v224
	s_nop 1
	v_addc_co_u32_e32 v227, vcc, 0, v225, vcc
	global_load_ushort v228, v[226:227], off
	v_add_co_u32_e32 v226, vcc, 0xb284000, v224
	s_nop 1
	v_addc_co_u32_e32 v227, vcc, 0, v225, vcc
	global_load_ushort v228, v[226:227], off
	v_add_co_u32_e32 v226, vcc, 0xb286000, v224
	s_nop 1
	v_addc_co_u32_e32 v227, vcc, 0, v225, vcc
	global_load_ushort v228, v[226:227], off
	s_branch .LBB0_1033
